# LayerNorm GEMM epilogues (out-proj and FFN-down): gamma/beta loads of all four column groups issued ahead, no vmcnt(0) behind the previous group's stores
# speedup vs baseline: 1.0002x; 1.0002x over previous
.LBB0_1776:
	s_or_b64 exec, exec, s[44:45]
	s_lshl_b32 s12, s16, 8
	s_or_b32 s12, s12, s7
	v_lshl_add_u32 v146, v176, 2, s12
	v_ashrrev_i32_e32 v147, 31, v146
	v_lshlrev_b64 v[136:137], 2, v[146:147]
	s_waitcnt lgkmcnt(0)
	s_barrier
	v_lshl_add_u64 v[66:67], s[52:53], 0, v[136:137]
	v_lshl_add_u64 v[158:159], s[54:55], 0, v[136:137]
	global_load_dwordx4 v[186:189], v[66:67], off
	global_load_dwordx4 v[190:193], v[158:159], off
	global_load_dwordx4 v[194:197], v[66:67], off offset:64
	global_load_dwordx4 v[198:201], v[158:159], off offset:64
	global_load_dwordx4 v[202:205], v[66:67], off offset:512
	global_load_dwordx4 v[228:231], v[158:159], off offset:512
	global_load_dwordx4 v[232:235], v[66:67], off offset:576
	global_load_dwordx4 v[236:239], v[158:159], off offset:576

	v_add_u32_e32 v148, s6, v65
	v_lshl_add_u32 v149, v148, 3, 0
	v_add_u32_e32 v177, 0x22000, v149
	ds_read_b64 v[150:151], v177
	s_waitcnt lgkmcnt(0)
	v_cmp_eq_u32_e32 vcc, 0, v178
	v_add_u32_e32 v162, v160, v148
	v_ashrrev_i32_e32 v163, 31, v162
	v_lshlrev_b64 v[160:161], 11, v[162:163]
	v_sub_f32_e32 v153, v1, v150
	v_sub_f32_e32 v152, v0, v150
	v_sub_f32_e32 v155, v3, v150
	v_sub_f32_e32 v154, v2, v150
	v_pk_mul_f32 v[154:155], v[150:151], v[154:155] op_sel:[1,0]
	v_pk_mul_f32 v[150:151], v[150:151], v[152:153] op_sel:[1,0]
	v_lshlrev_b64 v[146:147], 1, v[146:147]
	v_add_u32_e32 v148, 16, v162
	v_ashrrev_i32_e32 v149, 31, v148
	v_lshlrev_b64 v[148:149], 11, v[148:149]
	v_add_u32_e32 v170, 32, v162
	v_ashrrev_i32_e32 v171, 31, v170
	v_add_u32_e32 v168, 48, v162
	v_ashrrev_i32_e32 v169, 31, v168
	v_add_u32_e32 v166, 0x80, v162
	v_ashrrev_i32_e32 v167, 31, v166
	v_lshlrev_b64 v[182:183], 11, v[166:167]
	v_lshl_add_u64 v[166:167], s[10:11], 0, v[182:183]
	v_lshl_add_u64 v[166:167], v[166:167], 0, v[146:147]
	v_add_u32_e32 v164, 0x90, v162
	v_ashrrev_i32_e32 v165, 31, v164
	s_waitcnt vmcnt(0)
	v_pk_fma_f32 v[150:151], v[186:187], v[150:151], v[190:191]
	v_pk_fma_f32 v[152:153], v[188:189], v[154:155], v[192:193]
	v_cndmask_b32_e32 v150, v224, v150, vcc
	v_cndmask_b32_e32 v152, v224, v152, vcc
	v_cndmask_b32_e32 v153, v224, v153, vcc
	v_cndmask_b32_e32 v151, v224, v151, vcc
	v_cvt_pk_bf16_f32 v150, v150, v151
	v_cvt_pk_bf16_f32 v151, v152, v153
	ds_read_b64 v[152:153], v177 offset:128
	v_lshl_add_u64 v[154:155], s[10:11], 0, v[160:161]
	v_lshl_add_u64 v[154:155], v[154:155], 0, v[146:147]
	global_store_dwordx2 v[154:155], v[150:151], off
	s_waitcnt lgkmcnt(0)
	v_sub_f32_e32 v151, v9, v152
	v_sub_f32_e32 v150, v8, v152
	v_sub_f32_e32 v155, v11, v152
	v_sub_f32_e32 v154, v10, v152
	v_pk_mul_f32 v[154:155], v[152:153], v[154:155] op_sel:[1,0]
	v_pk_mul_f32 v[150:151], v[152:153], v[150:151] op_sel:[1,0]
	v_pk_fma_f32 v[152:153], v[188:189], v[154:155], v[192:193]
	v_pk_fma_f32 v[150:151], v[186:187], v[150:151], v[190:191]
	v_cndmask_b32_e32 v152, v224, v152, vcc
	v_cndmask_b32_e32 v153, v224, v153, vcc
	v_cndmask_b32_e32 v150, v224, v150, vcc
	v_cndmask_b32_e32 v151, v224, v151, vcc
	v_cvt_pk_bf16_f32 v150, v150, v151
	v_cvt_pk_bf16_f32 v151, v152, v153
	ds_read_b64 v[152:153], v177 offset:256
	v_lshl_add_u64 v[154:155], s[10:11], 0, v[148:149]
	v_lshl_add_u64 v[154:155], v[154:155], 0, v[146:147]
	global_store_dwordx2 v[154:155], v[150:151], off
	s_waitcnt lgkmcnt(0)
	v_sub_f32_e32 v151, v33, v152
	v_sub_f32_e32 v150, v32, v152
	v_sub_f32_e32 v155, v35, v152
	v_sub_f32_e32 v154, v34, v152
	v_pk_mul_f32 v[154:155], v[152:153], v[154:155] op_sel:[1,0]
	v_pk_mul_f32 v[150:151], v[152:153], v[150:151] op_sel:[1,0]
	v_pk_fma_f32 v[152:153], v[188:189], v[154:155], v[192:193]
	v_pk_fma_f32 v[150:151], v[186:187], v[150:151], v[190:191]
	v_cndmask_b32_e32 v152, v224, v152, vcc
	v_cndmask_b32_e32 v153, v224, v153, vcc
	v_cndmask_b32_e32 v150, v224, v150, vcc
	v_cndmask_b32_e32 v151, v224, v151, vcc
	v_cvt_pk_bf16_f32 v150, v150, v151
	v_cvt_pk_bf16_f32 v151, v152, v153
	ds_read_b64 v[152:153], v177 offset:384
	v_lshlrev_b64 v[154:155], 11, v[170:171]
	v_lshl_add_u64 v[170:171], s[10:11], 0, v[154:155]
	v_lshl_add_u64 v[170:171], v[170:171], 0, v[146:147]
	global_store_dwordx2 v[170:171], v[150:151], off
	s_waitcnt lgkmcnt(0)
	v_sub_f32_e32 v151, v49, v152
	v_sub_f32_e32 v150, v48, v152
	v_sub_f32_e32 v171, v51, v152
	v_sub_f32_e32 v170, v50, v152
	v_pk_mul_f32 v[170:171], v[152:153], v[170:171] op_sel:[1,0]
	v_pk_mul_f32 v[150:151], v[152:153], v[150:151] op_sel:[1,0]
	v_pk_fma_f32 v[152:153], v[188:189], v[170:171], v[192:193]
	v_pk_fma_f32 v[150:151], v[186:187], v[150:151], v[190:191]
	v_cndmask_b32_e32 v152, v224, v152, vcc
	v_cndmask_b32_e32 v153, v224, v153, vcc
	v_cndmask_b32_e32 v150, v224, v150, vcc
	v_cndmask_b32_e32 v151, v224, v151, vcc
	v_cvt_pk_bf16_f32 v150, v150, v151
	v_cvt_pk_bf16_f32 v151, v152, v153
	ds_read_b64 v[152:153], v177 offset:1024
	v_lshlrev_b64 v[170:171], 11, v[168:169]
	v_lshl_add_u64 v[168:169], s[10:11], 0, v[170:171]
	v_lshl_add_u64 v[168:169], v[168:169], 0, v[146:147]
	global_store_dwordx2 v[168:169], v[150:151], off
	s_waitcnt lgkmcnt(0)
	v_sub_f32_e32 v151, v69, v152
	v_sub_f32_e32 v150, v68, v152
	v_sub_f32_e32 v169, v71, v152
	v_sub_f32_e32 v168, v70, v152
	v_pk_mul_f32 v[168:169], v[152:153], v[168:169] op_sel:[1,0]
	v_pk_mul_f32 v[150:151], v[152:153], v[150:151] op_sel:[1,0]
	v_pk_fma_f32 v[152:153], v[188:189], v[168:169], v[192:193]
	v_pk_fma_f32 v[150:151], v[186:187], v[150:151], v[190:191]
	v_cndmask_b32_e32 v152, v224, v152, vcc
	v_cndmask_b32_e32 v153, v224, v153, vcc
	v_cndmask_b32_e32 v150, v224, v150, vcc
	v_cndmask_b32_e32 v151, v224, v151, vcc
	v_cvt_pk_bf16_f32 v150, v150, v151
	v_cvt_pk_bf16_f32 v151, v152, v153
	ds_read_b64 v[152:153], v177 offset:1152
	global_store_dwordx2 v[166:167], v[150:151], off
	s_waitcnt lgkmcnt(0)
	v_sub_f32_e32 v151, v85, v152
	v_sub_f32_e32 v150, v84, v152
	v_sub_f32_e32 v167, v87, v152
	v_sub_f32_e32 v166, v86, v152
	v_pk_mul_f32 v[150:151], v[152:153], v[150:151] op_sel:[1,0]
	v_pk_mul_f32 v[166:167], v[152:153], v[166:167] op_sel:[1,0]
	v_pk_fma_f32 v[150:151], v[186:187], v[150:151], v[190:191]
	v_pk_fma_f32 v[152:153], v[188:189], v[166:167], v[192:193]
	v_cndmask_b32_e32 v150, v224, v150, vcc
	v_cndmask_b32_e32 v151, v224, v151, vcc
	v_cndmask_b32_e32 v152, v224, v152, vcc
	v_cndmask_b32_e32 v153, v224, v153, vcc
	v_cvt_pk_bf16_f32 v150, v150, v151
	v_cvt_pk_bf16_f32 v151, v152, v153
	ds_read_b64 v[166:167], v177 offset:1280
	v_lshlrev_b64 v[152:153], 11, v[164:165]
	v_lshl_add_u64 v[164:165], s[10:11], 0, v[152:153]
	v_lshl_add_u64 v[164:165], v[164:165], 0, v[146:147]
	global_store_dwordx2 v[164:165], v[150:151], off
	s_waitcnt lgkmcnt(0)
	v_sub_f32_e32 v165, v101, v166
	v_sub_f32_e32 v164, v100, v166
	v_sub_f32_e32 v169, v103, v166
	v_sub_f32_e32 v168, v102, v166
	v_pk_mul_f32 v[164:165], v[166:167], v[164:165] op_sel:[1,0]
	v_pk_mul_f32 v[168:169], v[166:167], v[168:169] op_sel:[1,0]
	v_pk_fma_f32 v[164:165], v[186:187], v[164:165], v[190:191]
	v_pk_fma_f32 v[166:167], v[188:189], v[168:169], v[192:193]
	v_cndmask_b32_e32 v164, v224, v164, vcc
	v_cndmask_b32_e32 v165, v224, v165, vcc
	v_add_u32_e32 v150, 0xa0, v162
	v_cndmask_b32_e32 v163, v224, v166, vcc
	v_cndmask_b32_e32 v166, v224, v167, vcc
	v_cvt_pk_bf16_f32 v164, v164, v165
	v_cvt_pk_bf16_f32 v165, v163, v166
	ds_read_b64 v[168:169], v177 offset:1408
	v_ashrrev_i32_e32 v151, 31, v150
	v_lshlrev_b64 v[150:151], 11, v[150:151]
	v_lshl_add_u64 v[166:167], s[10:11], 0, v[150:151]
	v_lshl_add_u64 v[166:167], v[166:167], 0, v[146:147]
	global_store_dwordx2 v[166:167], v[164:165], off
	s_waitcnt lgkmcnt(0)
	v_sub_f32_e32 v165, v117, v168
	v_sub_f32_e32 v164, v116, v168
	v_sub_f32_e32 v167, v119, v168
	v_sub_f32_e32 v166, v118, v168
	v_add_u32_e32 v162, 0xb0, v162
	v_pk_mul_f32 v[166:167], v[168:169], v[166:167] op_sel:[1,0]
	v_pk_mul_f32 v[164:165], v[168:169], v[164:165] op_sel:[1,0]
	v_ashrrev_i32_e32 v163, 31, v162
	v_pk_fma_f32 v[132:133], v[186:187], v[164:165], v[190:191]
	v_pk_fma_f32 v[134:135], v[188:189], v[166:167], v[192:193]
	v_cndmask_b32_e32 v132, v224, v132, vcc
	v_cndmask_b32_e32 v134, v224, v134, vcc
	v_cndmask_b32_e32 v135, v224, v135, vcc
	v_cndmask_b32_e32 v133, v224, v133, vcc
	v_lshlrev_b64 v[184:185], 11, v[162:163]
	v_cvt_pk_bf16_f32 v132, v132, v133
	v_cvt_pk_bf16_f32 v133, v134, v135
	v_lshl_add_u64 v[134:135], s[10:11], 0, v[184:185]
	v_lshl_add_u64 v[134:135], v[134:135], 0, v[146:147]
	global_store_dwordx2 v[134:135], v[132:133], off


	ds_read_b64 v[132:133], v177
	v_lshl_add_u64 v[146:147], s[10:11], 0, v[146:147]
	v_lshl_add_u64 v[164:165], v[146:147], 0, v[150:151]
	s_waitcnt lgkmcnt(0)
	v_sub_f32_e32 v137, v7, v132
	v_sub_f32_e32 v136, v6, v132
	v_sub_f32_e32 v135, v5, v132
	v_sub_f32_e32 v134, v4, v132
	v_pk_mul_f32 v[136:137], v[132:133], v[136:137] op_sel:[1,0]
	v_pk_mul_f32 v[132:133], v[132:133], v[134:135] op_sel:[1,0]

	v_pk_fma_f32 v[134:135], v[196:197], v[136:137], v[200:201]
	v_pk_fma_f32 v[132:133], v[194:195], v[132:133], v[198:199]
	v_cndmask_b32_e32 v136, v224, v134, vcc
	v_cndmask_b32_e32 v135, v224, v135, vcc
	v_cndmask_b32_e32 v132, v224, v132, vcc
	v_cndmask_b32_e32 v133, v224, v133, vcc
	v_cvt_pk_bf16_f32 v134, v132, v133
	v_cvt_pk_bf16_f32 v135, v136, v135
	ds_read_b64 v[136:137], v177 offset:128
	v_lshl_add_u64 v[132:133], v[146:147], 0, v[160:161]
	global_store_dwordx2 v[132:133], v[134:135], off offset:32
	s_waitcnt lgkmcnt(0)
	v_sub_f32_e32 v139, v19, v136
	v_sub_f32_e32 v138, v18, v136
	v_sub_f32_e32 v135, v17, v136
	v_sub_f32_e32 v134, v16, v136
	v_pk_mul_f32 v[138:139], v[136:137], v[138:139] op_sel:[1,0]
	v_pk_mul_f32 v[134:135], v[136:137], v[134:135] op_sel:[1,0]
	v_pk_fma_f32 v[136:137], v[196:197], v[138:139], v[200:201]
	v_pk_fma_f32 v[134:135], v[194:195], v[134:135], v[198:199]
	v_cndmask_b32_e32 v138, v224, v136, vcc
	v_cndmask_b32_e32 v137, v224, v137, vcc
	v_cndmask_b32_e32 v134, v224, v134, vcc
	v_cndmask_b32_e32 v135, v224, v135, vcc
	v_cvt_pk_bf16_f32 v136, v134, v135
	v_cvt_pk_bf16_f32 v137, v138, v137
	ds_read_b64 v[138:139], v177 offset:256
	v_lshl_add_u64 v[134:135], v[146:147], 0, v[148:149]
	global_store_dwordx2 v[134:135], v[136:137], off offset:32
	s_waitcnt lgkmcnt(0)
	v_sub_f32_e32 v149, v39, v138
	v_sub_f32_e32 v148, v38, v138
	v_sub_f32_e32 v137, v37, v138
	v_sub_f32_e32 v136, v36, v138
	v_pk_mul_f32 v[148:149], v[138:139], v[148:149] op_sel:[1,0]
	v_pk_mul_f32 v[136:137], v[138:139], v[136:137] op_sel:[1,0]
	v_pk_fma_f32 v[138:139], v[196:197], v[148:149], v[200:201]
	v_pk_fma_f32 v[136:137], v[194:195], v[136:137], v[198:199]
	v_cndmask_b32_e32 v148, v224, v138, vcc
	v_cndmask_b32_e32 v139, v224, v139, vcc
	v_cndmask_b32_e32 v136, v224, v136, vcc
	v_cndmask_b32_e32 v137, v224, v137, vcc
	v_cvt_pk_bf16_f32 v138, v136, v137
	v_cvt_pk_bf16_f32 v139, v148, v139
	ds_read_b64 v[148:149], v177 offset:384
	v_lshl_add_u64 v[136:137], v[146:147], 0, v[154:155]
	global_store_dwordx2 v[136:137], v[138:139], off offset:32
	s_waitcnt lgkmcnt(0)
	v_sub_f32_e32 v155, v55, v148
	v_sub_f32_e32 v154, v54, v148
	v_sub_f32_e32 v139, v53, v148
	v_sub_f32_e32 v138, v52, v148
	v_pk_mul_f32 v[154:155], v[148:149], v[154:155] op_sel:[1,0]
	v_pk_mul_f32 v[138:139], v[148:149], v[138:139] op_sel:[1,0]
	v_pk_fma_f32 v[148:149], v[196:197], v[154:155], v[200:201]
	v_pk_fma_f32 v[138:139], v[194:195], v[138:139], v[198:199]
	v_cndmask_b32_e32 v154, v224, v148, vcc
	v_cndmask_b32_e32 v149, v224, v149, vcc
	v_cndmask_b32_e32 v138, v224, v138, vcc
	v_cndmask_b32_e32 v139, v224, v139, vcc
	v_cvt_pk_bf16_f32 v148, v138, v139
	v_cvt_pk_bf16_f32 v149, v154, v149
	ds_read_b64 v[154:155], v177 offset:1024
	v_lshl_add_u64 v[138:139], v[146:147], 0, v[170:171]
	global_store_dwordx2 v[138:139], v[148:149], off offset:32
	s_waitcnt lgkmcnt(0)
	v_sub_f32_e32 v149, v73, v154
	v_sub_f32_e32 v148, v72, v154
	v_sub_f32_e32 v161, v75, v154
	v_sub_f32_e32 v160, v74, v154
	v_pk_mul_f32 v[160:161], v[154:155], v[160:161] op_sel:[1,0]
	v_pk_mul_f32 v[148:149], v[154:155], v[148:149] op_sel:[1,0]
	v_pk_fma_f32 v[154:155], v[196:197], v[160:161], v[200:201]
	v_pk_fma_f32 v[148:149], v[194:195], v[148:149], v[198:199]
	v_cndmask_b32_e32 v154, v224, v154, vcc
	v_cndmask_b32_e32 v155, v224, v155, vcc
	v_cndmask_b32_e32 v148, v224, v148, vcc
	v_cndmask_b32_e32 v149, v224, v149, vcc
	v_cvt_pk_bf16_f32 v148, v148, v149
	v_cvt_pk_bf16_f32 v149, v154, v155
	ds_read_b64 v[154:155], v177 offset:1152
	v_lshl_add_u64 v[160:161], v[146:147], 0, v[182:183]
	global_store_dwordx2 v[160:161], v[148:149], off offset:32
	s_waitcnt lgkmcnt(0)
	v_sub_f32_e32 v149, v89, v154
	v_sub_f32_e32 v148, v88, v154
	v_sub_f32_e32 v163, v91, v154
	v_sub_f32_e32 v162, v90, v154
	v_pk_mul_f32 v[162:163], v[154:155], v[162:163] op_sel:[1,0]
	v_pk_mul_f32 v[148:149], v[154:155], v[148:149] op_sel:[1,0]
	v_pk_fma_f32 v[154:155], v[196:197], v[162:163], v[200:201]
	v_pk_fma_f32 v[148:149], v[194:195], v[148:149], v[198:199]
	v_cndmask_b32_e32 v154, v224, v154, vcc
	v_cndmask_b32_e32 v155, v224, v155, vcc
	v_cndmask_b32_e32 v148, v224, v148, vcc
	v_cndmask_b32_e32 v149, v224, v149, vcc
	v_cvt_pk_bf16_f32 v148, v148, v149
	v_cvt_pk_bf16_f32 v149, v154, v155
	ds_read_b64 v[154:155], v177 offset:1280
	v_lshl_add_u64 v[162:163], v[146:147], 0, v[152:153]
	global_store_dwordx2 v[162:163], v[148:149], off offset:32
	s_waitcnt lgkmcnt(0)
	v_sub_f32_e32 v149, v105, v154
	v_sub_f32_e32 v148, v104, v154
	v_sub_f32_e32 v153, v107, v154
	v_sub_f32_e32 v152, v106, v154
	v_pk_mul_f32 v[152:153], v[154:155], v[152:153] op_sel:[1,0]
	v_pk_mul_f32 v[148:149], v[154:155], v[148:149] op_sel:[1,0]
	v_pk_fma_f32 v[152:153], v[196:197], v[152:153], v[200:201]
	v_pk_fma_f32 v[148:149], v[194:195], v[148:149], v[198:199]
	v_cndmask_b32_e32 v152, v224, v152, vcc
	v_cndmask_b32_e32 v153, v224, v153, vcc
	v_cndmask_b32_e32 v148, v224, v148, vcc
	v_cndmask_b32_e32 v149, v224, v149, vcc
	v_cvt_pk_bf16_f32 v148, v148, v149
	v_cvt_pk_bf16_f32 v149, v152, v153
	ds_read_b64 v[152:153], v177 offset:1408
	global_store_dwordx2 v[164:165], v[148:149], off offset:32
	s_waitcnt lgkmcnt(0)
	v_sub_f32_e32 v149, v121, v152
	v_sub_f32_e32 v148, v120, v152
	v_sub_f32_e32 v151, v123, v152
	v_sub_f32_e32 v150, v122, v152
	v_pk_mul_f32 v[148:149], v[152:153], v[148:149] op_sel:[1,0]
	v_pk_mul_f32 v[150:151], v[152:153], v[150:151] op_sel:[1,0]
	v_pk_fma_f32 v[148:149], v[194:195], v[148:149], v[198:199]
	v_pk_fma_f32 v[150:151], v[196:197], v[150:151], v[200:201]
	v_cndmask_b32_e32 v148, v224, v148, vcc
	v_cndmask_b32_e32 v149, v224, v149, vcc
	v_lshl_add_u64 v[166:167], v[146:147], 0, v[184:185]
	v_cndmask_b32_e32 v150, v224, v150, vcc
	v_cndmask_b32_e32 v151, v224, v151, vcc
	v_cvt_pk_bf16_f32 v148, v148, v149
	v_cvt_pk_bf16_f32 v149, v150, v151
	global_store_dwordx2 v[166:167], v[148:149], off offset:32


	ds_read_b64 v[146:147], v177
	s_waitcnt lgkmcnt(0)
	v_sub_f32_e32 v149, v13, v146
	v_sub_f32_e32 v148, v12, v146
	v_sub_f32_e32 v151, v15, v146
	v_sub_f32_e32 v150, v14, v146
	v_pk_mul_f32 v[150:151], v[146:147], v[150:151] op_sel:[1,0]
	v_pk_mul_f32 v[146:147], v[146:147], v[148:149] op_sel:[1,0]

	v_pk_fma_f32 v[148:149], v[204:205], v[150:151], v[230:231]
	v_pk_fma_f32 v[146:147], v[202:203], v[146:147], v[228:229]
	v_cndmask_b32_e32 v148, v224, v148, vcc
	v_cndmask_b32_e32 v149, v224, v149, vcc
	v_cndmask_b32_e32 v146, v224, v146, vcc
	v_cndmask_b32_e32 v147, v224, v147, vcc
	v_cvt_pk_bf16_f32 v146, v146, v147
	v_cvt_pk_bf16_f32 v147, v148, v149
	ds_read_b64 v[148:149], v177 offset:128
	global_store_dwordx2 v[132:133], v[146:147], off offset:256
	s_waitcnt lgkmcnt(0)
	v_sub_f32_e32 v147, v25, v148
	v_sub_f32_e32 v146, v24, v148
	v_sub_f32_e32 v151, v27, v148
	v_sub_f32_e32 v150, v26, v148
	v_pk_mul_f32 v[150:151], v[148:149], v[150:151] op_sel:[1,0]
	v_pk_mul_f32 v[146:147], v[148:149], v[146:147] op_sel:[1,0]
	v_pk_fma_f32 v[148:149], v[204:205], v[150:151], v[230:231]
	v_pk_fma_f32 v[146:147], v[202:203], v[146:147], v[228:229]
	v_cndmask_b32_e32 v148, v224, v148, vcc
	v_cndmask_b32_e32 v149, v224, v149, vcc
	v_cndmask_b32_e32 v146, v224, v146, vcc
	v_cndmask_b32_e32 v147, v224, v147, vcc
	v_cvt_pk_bf16_f32 v146, v146, v147
	v_cvt_pk_bf16_f32 v147, v148, v149
	ds_read_b64 v[148:149], v177 offset:256
	global_store_dwordx2 v[134:135], v[146:147], off offset:256
	s_waitcnt lgkmcnt(0)
	v_sub_f32_e32 v147, v41, v148
	v_sub_f32_e32 v146, v40, v148
	v_sub_f32_e32 v151, v43, v148
	v_sub_f32_e32 v150, v42, v148
	v_pk_mul_f32 v[150:151], v[148:149], v[150:151] op_sel:[1,0]
	v_pk_mul_f32 v[146:147], v[148:149], v[146:147] op_sel:[1,0]
	v_pk_fma_f32 v[148:149], v[204:205], v[150:151], v[230:231]
	v_pk_fma_f32 v[146:147], v[202:203], v[146:147], v[228:229]
	v_cndmask_b32_e32 v148, v224, v148, vcc
	v_cndmask_b32_e32 v149, v224, v149, vcc
	v_cndmask_b32_e32 v146, v224, v146, vcc
	v_cndmask_b32_e32 v147, v224, v147, vcc
	v_cvt_pk_bf16_f32 v146, v146, v147
	v_cvt_pk_bf16_f32 v147, v148, v149
	ds_read_b64 v[148:149], v177 offset:384
	global_store_dwordx2 v[136:137], v[146:147], off offset:256
	s_waitcnt lgkmcnt(0)
	v_sub_f32_e32 v147, v57, v148
	v_sub_f32_e32 v146, v56, v148
	v_sub_f32_e32 v151, v59, v148
	v_sub_f32_e32 v150, v58, v148
	v_pk_mul_f32 v[150:151], v[148:149], v[150:151] op_sel:[1,0]
	v_pk_mul_f32 v[146:147], v[148:149], v[146:147] op_sel:[1,0]
	v_pk_fma_f32 v[148:149], v[204:205], v[150:151], v[230:231]
	v_pk_fma_f32 v[146:147], v[202:203], v[146:147], v[228:229]
	v_cndmask_b32_e32 v148, v224, v148, vcc
	v_cndmask_b32_e32 v149, v224, v149, vcc
	v_cndmask_b32_e32 v146, v224, v146, vcc
	v_cndmask_b32_e32 v147, v224, v147, vcc
	v_cvt_pk_bf16_f32 v146, v146, v147
	v_cvt_pk_bf16_f32 v147, v148, v149
	ds_read_b64 v[148:149], v177 offset:1024
	global_store_dwordx2 v[138:139], v[146:147], off offset:256
	s_waitcnt lgkmcnt(0)
	v_sub_f32_e32 v147, v77, v148
	v_sub_f32_e32 v146, v76, v148
	v_sub_f32_e32 v151, v79, v148
	v_sub_f32_e32 v150, v78, v148
	v_pk_mul_f32 v[150:151], v[148:149], v[150:151] op_sel:[1,0]
	v_pk_mul_f32 v[146:147], v[148:149], v[146:147] op_sel:[1,0]
	v_pk_fma_f32 v[148:149], v[204:205], v[150:151], v[230:231]
	v_pk_fma_f32 v[146:147], v[202:203], v[146:147], v[228:229]
	v_cndmask_b32_e32 v148, v224, v148, vcc
	v_cndmask_b32_e32 v149, v224, v149, vcc
	v_cndmask_b32_e32 v146, v224, v146, vcc
	v_cndmask_b32_e32 v147, v224, v147, vcc
	v_cvt_pk_bf16_f32 v146, v146, v147
	v_cvt_pk_bf16_f32 v147, v148, v149
	ds_read_b64 v[148:149], v177 offset:1152
	global_store_dwordx2 v[160:161], v[146:147], off offset:256
	s_waitcnt lgkmcnt(0)
	v_sub_f32_e32 v147, v93, v148
	v_sub_f32_e32 v146, v92, v148
	v_sub_f32_e32 v151, v95, v148
	v_sub_f32_e32 v150, v94, v148
	v_pk_mul_f32 v[150:151], v[148:149], v[150:151] op_sel:[1,0]
	v_pk_mul_f32 v[146:147], v[148:149], v[146:147] op_sel:[1,0]
	v_pk_fma_f32 v[148:149], v[204:205], v[150:151], v[230:231]
	v_pk_fma_f32 v[146:147], v[202:203], v[146:147], v[228:229]
	v_cndmask_b32_e32 v148, v224, v148, vcc
	v_cndmask_b32_e32 v149, v224, v149, vcc
	v_cndmask_b32_e32 v146, v224, v146, vcc
	v_cndmask_b32_e32 v147, v224, v147, vcc
	v_cvt_pk_bf16_f32 v146, v146, v147
	v_cvt_pk_bf16_f32 v147, v148, v149
	ds_read_b64 v[148:149], v177 offset:1280
	global_store_dwordx2 v[162:163], v[146:147], off offset:256
	s_waitcnt lgkmcnt(0)
	v_sub_f32_e32 v147, v109, v148
	v_sub_f32_e32 v146, v108, v148
	v_sub_f32_e32 v151, v111, v148
	v_sub_f32_e32 v150, v110, v148
	v_pk_mul_f32 v[150:151], v[148:149], v[150:151] op_sel:[1,0]
	v_pk_mul_f32 v[146:147], v[148:149], v[146:147] op_sel:[1,0]
	v_pk_fma_f32 v[148:149], v[204:205], v[150:151], v[230:231]
	v_pk_fma_f32 v[146:147], v[202:203], v[146:147], v[228:229]
	v_cndmask_b32_e32 v148, v224, v148, vcc
	v_cndmask_b32_e32 v149, v224, v149, vcc
	v_cndmask_b32_e32 v146, v224, v146, vcc
	v_cndmask_b32_e32 v147, v224, v147, vcc
	v_cvt_pk_bf16_f32 v146, v146, v147
	v_cvt_pk_bf16_f32 v147, v148, v149
	ds_read_b64 v[148:149], v177 offset:1408
	global_store_dwordx2 v[164:165], v[146:147], off offset:256
	s_waitcnt lgkmcnt(0)
	v_sub_f32_e32 v147, v125, v148
	v_sub_f32_e32 v146, v124, v148
	v_sub_f32_e32 v151, v127, v148
	v_sub_f32_e32 v150, v126, v148
	v_pk_mul_f32 v[146:147], v[148:149], v[146:147] op_sel:[1,0]
	v_pk_mul_f32 v[150:151], v[148:149], v[150:151] op_sel:[1,0]
	v_pk_fma_f32 v[146:147], v[202:203], v[146:147], v[228:229]
	v_pk_fma_f32 v[148:149], v[204:205], v[150:151], v[230:231]
	v_cndmask_b32_e32 v146, v224, v146, vcc
	v_cndmask_b32_e32 v147, v224, v147, vcc
	v_cndmask_b32_e32 v148, v224, v148, vcc
	v_cndmask_b32_e32 v149, v224, v149, vcc
	v_cvt_pk_bf16_f32 v146, v146, v147
	v_cvt_pk_bf16_f32 v147, v148, v149
	global_store_dwordx2 v[166:167], v[146:147], off offset:256


	ds_read_b64 v[66:67], v177
	s_waitcnt lgkmcnt(0)
	v_sub_f32_e32 v147, v21, v66
	v_sub_f32_e32 v146, v20, v66
	v_sub_f32_e32 v149, v23, v66
	v_sub_f32_e32 v148, v22, v66
	v_pk_mul_f32 v[148:149], v[66:67], v[148:149] op_sel:[1,0]
	v_pk_mul_f32 v[66:67], v[66:67], v[146:147] op_sel:[1,0]

	v_pk_fma_f32 v[146:147], v[234:235], v[148:149], v[238:239]
	v_pk_fma_f32 v[66:67], v[232:233], v[66:67], v[236:237]
	v_cndmask_b32_e32 v146, v224, v146, vcc
	v_cndmask_b32_e32 v147, v224, v147, vcc
	v_cndmask_b32_e32 v66, v224, v66, vcc
	v_cndmask_b32_e32 v67, v224, v67, vcc
	v_cvt_pk_bf16_f32 v66, v66, v67
	v_cvt_pk_bf16_f32 v67, v146, v147
	ds_read_b64 v[146:147], v177 offset:128
	global_store_dwordx2 v[132:133], v[66:67], off offset:288
	s_waitcnt lgkmcnt(0)
	v_sub_f32_e32 v67, v29, v146
	v_sub_f32_e32 v66, v28, v146
	v_sub_f32_e32 v133, v31, v146
	v_sub_f32_e32 v132, v30, v146
	v_pk_mul_f32 v[132:133], v[146:147], v[132:133] op_sel:[1,0]
	v_pk_mul_f32 v[66:67], v[146:147], v[66:67] op_sel:[1,0]
	v_pk_fma_f32 v[132:133], v[234:235], v[132:133], v[238:239]
	v_pk_fma_f32 v[66:67], v[232:233], v[66:67], v[236:237]
	v_cndmask_b32_e32 v132, v224, v132, vcc
	v_cndmask_b32_e32 v133, v224, v133, vcc
	v_cndmask_b32_e32 v66, v224, v66, vcc
	v_cndmask_b32_e32 v67, v224, v67, vcc
	v_cvt_pk_bf16_f32 v66, v66, v67
	v_cvt_pk_bf16_f32 v67, v132, v133
	ds_read_b64 v[132:133], v177 offset:256
	global_store_dwordx2 v[134:135], v[66:67], off offset:288
	s_waitcnt lgkmcnt(0)
	v_sub_f32_e32 v67, v45, v132
	v_sub_f32_e32 v66, v44, v132
	v_sub_f32_e32 v135, v47, v132
	v_sub_f32_e32 v134, v46, v132
	v_pk_mul_f32 v[134:135], v[132:133], v[134:135] op_sel:[1,0]
	v_pk_mul_f32 v[66:67], v[132:133], v[66:67] op_sel:[1,0]
	v_pk_fma_f32 v[132:133], v[234:235], v[134:135], v[238:239]
	v_pk_fma_f32 v[66:67], v[232:233], v[66:67], v[236:237]
	v_cndmask_b32_e32 v132, v224, v132, vcc
	v_cndmask_b32_e32 v133, v224, v133, vcc
	v_cndmask_b32_e32 v66, v224, v66, vcc
	v_cndmask_b32_e32 v67, v224, v67, vcc
	v_cvt_pk_bf16_f32 v66, v66, v67
	v_cvt_pk_bf16_f32 v67, v132, v133
	ds_read_b64 v[132:133], v177 offset:384
	global_store_dwordx2 v[136:137], v[66:67], off offset:288
	s_waitcnt lgkmcnt(0)
	v_sub_f32_e32 v67, v61, v132
	v_sub_f32_e32 v66, v60, v132
	v_sub_f32_e32 v135, v63, v132
	v_sub_f32_e32 v134, v62, v132
	v_pk_mul_f32 v[134:135], v[132:133], v[134:135] op_sel:[1,0]
	v_pk_mul_f32 v[66:67], v[132:133], v[66:67] op_sel:[1,0]
	v_pk_fma_f32 v[132:133], v[234:235], v[134:135], v[238:239]
	v_pk_fma_f32 v[66:67], v[232:233], v[66:67], v[236:237]
	v_cndmask_b32_e32 v132, v224, v132, vcc
	v_cndmask_b32_e32 v133, v224, v133, vcc
	v_cndmask_b32_e32 v66, v224, v66, vcc
	v_cndmask_b32_e32 v67, v224, v67, vcc
	v_cvt_pk_bf16_f32 v66, v66, v67
	v_cvt_pk_bf16_f32 v67, v132, v133
	ds_read_b64 v[132:133], v177 offset:1024
	global_store_dwordx2 v[138:139], v[66:67], off offset:288
	s_waitcnt lgkmcnt(0)
	v_sub_f32_e32 v67, v81, v132
	v_sub_f32_e32 v66, v80, v132
	v_sub_f32_e32 v135, v83, v132
	v_sub_f32_e32 v134, v82, v132
	v_pk_mul_f32 v[134:135], v[132:133], v[134:135] op_sel:[1,0]
	v_pk_mul_f32 v[66:67], v[132:133], v[66:67] op_sel:[1,0]
	v_pk_fma_f32 v[132:133], v[234:235], v[134:135], v[238:239]
	v_pk_fma_f32 v[66:67], v[232:233], v[66:67], v[236:237]
	v_cndmask_b32_e32 v132, v224, v132, vcc
	v_cndmask_b32_e32 v133, v224, v133, vcc
	v_cndmask_b32_e32 v66, v224, v66, vcc
	v_cndmask_b32_e32 v67, v224, v67, vcc
	v_cvt_pk_bf16_f32 v66, v66, v67
	v_cvt_pk_bf16_f32 v67, v132, v133
	ds_read_b64 v[132:133], v177 offset:1152
	global_store_dwordx2 v[160:161], v[66:67], off offset:288
	s_waitcnt lgkmcnt(0)
	v_sub_f32_e32 v67, v97, v132
	v_sub_f32_e32 v66, v96, v132
	v_sub_f32_e32 v135, v99, v132
	v_sub_f32_e32 v134, v98, v132
	v_pk_mul_f32 v[134:135], v[132:133], v[134:135] op_sel:[1,0]
	v_pk_mul_f32 v[66:67], v[132:133], v[66:67] op_sel:[1,0]
	v_pk_fma_f32 v[132:133], v[234:235], v[134:135], v[238:239]
	v_pk_fma_f32 v[66:67], v[232:233], v[66:67], v[236:237]
	v_cndmask_b32_e32 v132, v224, v132, vcc
	v_cndmask_b32_e32 v133, v224, v133, vcc
	v_cndmask_b32_e32 v66, v224, v66, vcc
	v_cndmask_b32_e32 v67, v224, v67, vcc
	v_cvt_pk_bf16_f32 v66, v66, v67
	v_cvt_pk_bf16_f32 v67, v132, v133
	ds_read_b64 v[132:133], v177 offset:1280
	global_store_dwordx2 v[162:163], v[66:67], off offset:288
	s_waitcnt lgkmcnt(0)
	v_sub_f32_e32 v67, v113, v132
	v_sub_f32_e32 v66, v112, v132
	v_sub_f32_e32 v135, v115, v132
	v_sub_f32_e32 v134, v114, v132
	v_pk_mul_f32 v[134:135], v[132:133], v[134:135] op_sel:[1,0]
	v_pk_mul_f32 v[66:67], v[132:133], v[66:67] op_sel:[1,0]
	v_pk_fma_f32 v[132:133], v[234:235], v[134:135], v[238:239]
	v_pk_fma_f32 v[66:67], v[232:233], v[66:67], v[236:237]
	v_cndmask_b32_e32 v132, v224, v132, vcc
	v_cndmask_b32_e32 v133, v224, v133, vcc
	v_cndmask_b32_e32 v66, v224, v66, vcc
	v_cndmask_b32_e32 v67, v224, v67, vcc
	v_cvt_pk_bf16_f32 v66, v66, v67
	v_cvt_pk_bf16_f32 v67, v132, v133
	ds_read_b64 v[132:133], v177 offset:1408
	global_store_dwordx2 v[164:165], v[66:67], off offset:288
	s_waitcnt lgkmcnt(0)
	v_sub_f32_e32 v67, v129, v132
	v_sub_f32_e32 v66, v128, v132
	v_sub_f32_e32 v135, v131, v132
	v_sub_f32_e32 v134, v130, v132
	v_pk_mul_f32 v[66:67], v[132:133], v[66:67] op_sel:[1,0]
	v_pk_mul_f32 v[134:135], v[132:133], v[134:135] op_sel:[1,0]
	v_pk_fma_f32 v[66:67], v[232:233], v[66:67], v[236:237]
	v_pk_fma_f32 v[132:133], v[234:235], v[134:135], v[238:239]
	v_cndmask_b32_e32 v66, v224, v66, vcc
	v_cndmask_b32_e32 v67, v224, v67, vcc
	v_cndmask_b32_e32 v132, v224, v132, vcc
	v_cndmask_b32_e32 v133, v224, v133, vcc
	v_cvt_pk_bf16_f32 v66, v66, v67
	v_cvt_pk_bf16_f32 v67, v132, v133
	global_store_dwordx2 v[166:167], v[66:67], off offset:288
	s_waitcnt lgkmcnt(0)
	s_barrier
	s_branch .LBB0_1758

.LBB0_2038:
	s_or_b64 exec, exec, s[44:45]
	s_lshl_b32 s3, s16, 8
	s_or_b32 s3, s3, s76
	v_lshl_add_u32 v66, v204, 2, s3
	v_ashrrev_i32_e32 v67, 31, v66
	v_lshlrev_b64 v[136:137], 2, v[66:67]
	s_waitcnt lgkmcnt(0)
	s_barrier
	v_lshl_add_u64 v[164:165], s[54:55], 0, v[136:137]
	v_lshl_add_u64 v[166:167], s[56:57], 0, v[136:137]
	s_waitcnt lgkmcnt(0)
	v_cmp_eq_u32_e64 s[42:43], 0, v133
	global_load_dwordx4 v[132:135], v[164:165], off
	global_load_dwordx4 v[136:139], v[166:167], off
	global_load_dwordx4 v[228:231], v[164:165], off offset:64
	global_load_dwordx4 v[232:235], v[166:167], off offset:64
	v_add_u32_e32 v141, s31, v65
	v_lshl_add_u32 v142, v141, 3, 0
	v_add_u32_e32 v205, 0x22000, v142
	ds_read_b64 v[142:143], v205
	v_add_u32_e32 v180, v140, v141
	v_ashrrev_i32_e32 v181, 31, v180
	v_lshlrev_b64 v[162:163], 10, v[180:181]
	v_lshl_add_u64 v[168:169], v[162:163], 0, v[66:67]
	s_waitcnt lgkmcnt(0)
	v_sub_f32_e32 v141, v3, v142
	v_sub_f32_e32 v140, v2, v142
	v_sub_f32_e32 v147, v1, v142
	v_sub_f32_e32 v146, v0, v142
	v_pk_mul_f32 v[146:147], v[142:143], v[146:147] op_sel:[1,0]
	v_pk_mul_f32 v[140:141], v[142:143], v[140:141] op_sel:[1,0]
	s_mov_b64 s[12:13], -1
	s_andn2_b64 vcc, exec, s[60:61]
	v_lshl_add_u64 v[182:183], v[168:169], 2, s[48:49]
	s_waitcnt vmcnt(2)
	v_pk_fma_f32 v[142:143], v[134:135], v[140:141], v[138:139]
	v_pk_fma_f32 v[140:141], v[132:133], v[146:147], v[136:137]
	v_cndmask_b32_e64 v146, 0, 1, s[60:61]
	v_cndmask_b32_e64 v141, v224, v141, s[42:43]
	v_cndmask_b32_e64 v140, v224, v140, s[42:43]
	v_cndmask_b32_e64 v143, v224, v143, s[42:43]
	v_cndmask_b32_e64 v142, v224, v142, s[42:43]
	v_cmp_ne_u32_e64 s[44:45], 1, v146
	s_cbranch_vccnz .LBB0_2040
	s_mov_b64 s[12:13], 0
	global_store_dwordx4 v[182:183], v[140:143], off nt

.LBB0_2070:
	global_load_dwordx4 v[132:135], v[164:165], off offset:512
	global_load_dwordx4 v[136:139], v[166:167], off offset:512
	ds_read_b64 v[140:141], v205
	s_and_b64 vcc, exec, s[44:45]
	s_mov_b64 s[12:13], -1
	s_waitcnt lgkmcnt(0)
	v_sub_f32_e32 v143, v5, v140
	v_sub_f32_e32 v142, v4, v140
	v_sub_f32_e32 v147, v7, v140
	v_sub_f32_e32 v146, v6, v140
	v_pk_mul_f32 v[146:147], v[140:141], v[146:147] op_sel:[1,0]
	v_pk_mul_f32 v[140:141], v[140:141], v[142:143] op_sel:[1,0]
	s_waitcnt vmcnt(10)
	v_pk_fma_f32 v[142:143], v[230:231], v[146:147], v[234:235]
	v_pk_fma_f32 v[140:141], v[228:229], v[140:141], v[232:233]
	v_cndmask_b32_e64 v143, v224, v143, s[42:43]
	v_cndmask_b32_e64 v142, v224, v142, s[42:43]
	v_cndmask_b32_e64 v141, v224, v141, s[42:43]
	v_cndmask_b32_e64 v140, v224, v140, s[42:43]
	s_cbranch_vccnz .LBB0_2072
	s_mov_b64 s[12:13], 0
	global_store_dwordx4 v[182:183], v[140:143], off offset:64 nt

.LBB0_2074:
	ds_read_b64 v[140:141], v205 offset:128
	s_and_b64 vcc, exec, s[44:45]
	s_mov_b64 s[12:13], -1
	s_waitcnt lgkmcnt(0)
	v_sub_f32_e32 v143, v17, v140
	v_sub_f32_e32 v142, v16, v140
	v_sub_f32_e32 v147, v19, v140
	v_sub_f32_e32 v146, v18, v140
	v_pk_mul_f32 v[146:147], v[140:141], v[146:147] op_sel:[1,0]
	v_pk_mul_f32 v[140:141], v[140:141], v[142:143] op_sel:[1,0]
	v_pk_fma_f32 v[142:143], v[230:231], v[146:147], v[234:235]
	v_pk_fma_f32 v[140:141], v[228:229], v[140:141], v[232:233]
	v_cndmask_b32_e64 v143, v224, v143, s[42:43]
	v_cndmask_b32_e64 v142, v224, v142, s[42:43]
	v_cndmask_b32_e64 v141, v224, v141, s[42:43]
	v_cndmask_b32_e64 v140, v224, v140, s[42:43]
	s_cbranch_vccnz .LBB0_2076
	s_mov_b64 s[12:13], 0
	global_store_dwordx4 v[184:185], v[140:143], off offset:64 nt

.LBB0_2078:
	ds_read_b64 v[140:141], v205 offset:256
	s_and_b64 vcc, exec, s[44:45]
	s_mov_b64 s[12:13], -1
	s_waitcnt lgkmcnt(0)
	v_sub_f32_e32 v143, v37, v140
	v_sub_f32_e32 v142, v36, v140
	v_sub_f32_e32 v147, v39, v140
	v_sub_f32_e32 v146, v38, v140
	v_pk_mul_f32 v[146:147], v[140:141], v[146:147] op_sel:[1,0]
	v_pk_mul_f32 v[140:141], v[140:141], v[142:143] op_sel:[1,0]
	v_pk_fma_f32 v[142:143], v[230:231], v[146:147], v[234:235]
	v_pk_fma_f32 v[140:141], v[228:229], v[140:141], v[232:233]
	v_cndmask_b32_e64 v143, v224, v143, s[42:43]
	v_cndmask_b32_e64 v142, v224, v142, s[42:43]
	v_cndmask_b32_e64 v141, v224, v141, s[42:43]
	v_cndmask_b32_e64 v140, v224, v140, s[42:43]
	s_cbranch_vccnz .LBB0_2080
	s_mov_b64 s[12:13], 0
	global_store_dwordx4 v[186:187], v[140:143], off offset:64 nt

.LBB0_2082:
	ds_read_b64 v[140:141], v205 offset:384
	s_and_b64 vcc, exec, s[44:45]
	s_mov_b64 s[12:13], -1
	s_waitcnt lgkmcnt(0)
	v_sub_f32_e32 v143, v53, v140
	v_sub_f32_e32 v142, v52, v140
	v_sub_f32_e32 v147, v55, v140
	v_sub_f32_e32 v146, v54, v140
	v_pk_mul_f32 v[146:147], v[140:141], v[146:147] op_sel:[1,0]
	v_pk_mul_f32 v[140:141], v[140:141], v[142:143] op_sel:[1,0]
	v_pk_fma_f32 v[142:143], v[230:231], v[146:147], v[234:235]
	v_pk_fma_f32 v[140:141], v[228:229], v[140:141], v[232:233]
	v_cndmask_b32_e64 v143, v224, v143, s[42:43]
	v_cndmask_b32_e64 v142, v224, v142, s[42:43]
	v_cndmask_b32_e64 v141, v224, v141, s[42:43]
	v_cndmask_b32_e64 v140, v224, v140, s[42:43]
	s_cbranch_vccnz .LBB0_2084
	s_mov_b64 s[12:13], 0
	global_store_dwordx4 v[188:189], v[140:143], off offset:64 nt

.LBB0_2086:
	ds_read_b64 v[140:141], v205 offset:1024
	s_and_b64 vcc, exec, s[44:45]
	s_mov_b64 s[12:13], -1
	s_waitcnt lgkmcnt(0)
	v_sub_f32_e32 v143, v73, v140
	v_sub_f32_e32 v142, v72, v140
	v_sub_f32_e32 v147, v75, v140
	v_sub_f32_e32 v146, v74, v140
	v_pk_mul_f32 v[146:147], v[140:141], v[146:147] op_sel:[1,0]
	v_pk_mul_f32 v[140:141], v[140:141], v[142:143] op_sel:[1,0]
	v_pk_fma_f32 v[142:143], v[230:231], v[146:147], v[234:235]
	v_pk_fma_f32 v[140:141], v[228:229], v[140:141], v[232:233]
	v_cndmask_b32_e64 v143, v224, v143, s[42:43]
	v_cndmask_b32_e64 v142, v224, v142, s[42:43]
	v_cndmask_b32_e64 v141, v224, v141, s[42:43]
	v_cndmask_b32_e64 v140, v224, v140, s[42:43]
	s_cbranch_vccnz .LBB0_2088
	s_mov_b64 s[12:13], 0
	global_store_dwordx4 v[190:191], v[140:143], off offset:64 nt

.LBB0_2090:
	ds_read_b64 v[140:141], v205 offset:1152
	s_and_b64 vcc, exec, s[44:45]
	s_mov_b64 s[12:13], -1
	s_waitcnt lgkmcnt(0)
	v_sub_f32_e32 v143, v89, v140
	v_sub_f32_e32 v142, v88, v140
	v_sub_f32_e32 v147, v91, v140
	v_sub_f32_e32 v146, v90, v140
	v_pk_mul_f32 v[146:147], v[140:141], v[146:147] op_sel:[1,0]
	v_pk_mul_f32 v[140:141], v[140:141], v[142:143] op_sel:[1,0]
	v_pk_fma_f32 v[142:143], v[230:231], v[146:147], v[234:235]
	v_pk_fma_f32 v[140:141], v[228:229], v[140:141], v[232:233]
	v_cndmask_b32_e64 v143, v224, v143, s[42:43]
	v_cndmask_b32_e64 v142, v224, v142, s[42:43]
	v_cndmask_b32_e64 v141, v224, v141, s[42:43]
	v_cndmask_b32_e64 v140, v224, v140, s[42:43]
	s_cbranch_vccnz .LBB0_2092
	s_mov_b64 s[12:13], 0
	global_store_dwordx4 v[192:193], v[140:143], off offset:64 nt

.LBB0_2094:
	ds_read_b64 v[140:141], v205 offset:1280
	s_and_b64 vcc, exec, s[44:45]
	s_mov_b64 s[12:13], -1
	s_waitcnt lgkmcnt(0)
	v_sub_f32_e32 v143, v105, v140
	v_sub_f32_e32 v142, v104, v140
	v_sub_f32_e32 v147, v107, v140
	v_sub_f32_e32 v146, v106, v140
	v_pk_mul_f32 v[146:147], v[140:141], v[146:147] op_sel:[1,0]
	v_pk_mul_f32 v[140:141], v[140:141], v[142:143] op_sel:[1,0]
	v_pk_fma_f32 v[142:143], v[230:231], v[146:147], v[234:235]
	v_pk_fma_f32 v[140:141], v[228:229], v[140:141], v[232:233]
	v_cndmask_b32_e64 v143, v224, v143, s[42:43]
	v_cndmask_b32_e64 v142, v224, v142, s[42:43]
	v_cndmask_b32_e64 v141, v224, v141, s[42:43]
	v_cndmask_b32_e64 v140, v224, v140, s[42:43]
	s_cbranch_vccnz .LBB0_2096
	s_mov_b64 s[12:13], 0
	global_store_dwordx4 v[194:195], v[140:143], off offset:64 nt

.LBB0_2098:
	ds_read_b64 v[140:141], v205 offset:1408
	s_and_b64 vcc, exec, s[44:45]
	s_mov_b64 s[12:13], -1
	s_waitcnt lgkmcnt(0)
	v_sub_f32_e32 v143, v121, v140
	v_sub_f32_e32 v142, v120, v140
	v_sub_f32_e32 v147, v123, v140
	v_sub_f32_e32 v146, v122, v140
	v_pk_mul_f32 v[146:147], v[140:141], v[146:147] op_sel:[1,0]
	v_pk_mul_f32 v[140:141], v[140:141], v[142:143] op_sel:[1,0]
	v_pk_fma_f32 v[230:231], v[230:231], v[146:147], v[234:235]
	v_pk_fma_f32 v[228:229], v[228:229], v[140:141], v[232:233]
	v_cndmask_b32_e64 v231, v224, v231, s[42:43]
	v_cndmask_b32_e64 v230, v224, v230, s[42:43]
	v_cndmask_b32_e64 v229, v224, v229, s[42:43]
	v_cndmask_b32_e64 v228, v224, v228, s[42:43]
	s_cbranch_vccnz .LBB0_2100
	s_mov_b64 s[12:13], 0
	global_store_dwordx4 v[196:197], v[228:231], off offset:64 nt
.LBB0_2100:
	s_andn2_b64 vcc, exec, s[12:13]
	s_cbranch_vccnz .LBB0_2102
	v_lshl_add_u64 v[232:233], v[180:181], 0, v[198:199]
	v_cvt_pk_bf16_f32 v228, v228, v229
	v_cvt_pk_bf16_f32 v229, v230, v231
	v_lshl_add_u64 v[230:231], v[232:233], 1, s[10:11]
	global_store_dwordx2 v[230:231], v[228:229], off
.LBB0_2102:
	global_load_dwordx4 v[228:231], v[164:165], off offset:576
	global_load_dwordx4 v[232:235], v[166:167], off offset:576
	ds_read_b64 v[140:141], v205
	s_and_b64 vcc, exec, s[44:45]
	s_mov_b64 s[12:13], -1
	s_waitcnt lgkmcnt(0)
	v_sub_f32_e32 v143, v13, v140
	v_sub_f32_e32 v142, v12, v140
	v_sub_f32_e32 v147, v15, v140
	v_sub_f32_e32 v146, v14, v140
	v_pk_mul_f32 v[146:147], v[140:141], v[146:147] op_sel:[1,0]
	v_pk_mul_f32 v[140:141], v[140:141], v[142:143] op_sel:[1,0]
	s_waitcnt vmcnt(10)
	v_pk_fma_f32 v[142:143], v[134:135], v[146:147], v[138:139]
	v_pk_fma_f32 v[140:141], v[132:133], v[140:141], v[136:137]
	v_cndmask_b32_e64 v143, v224, v143, s[42:43]
	v_cndmask_b32_e64 v142, v224, v142, s[42:43]
	v_cndmask_b32_e64 v141, v224, v141, s[42:43]
	v_cndmask_b32_e64 v140, v224, v140, s[42:43]
	s_cbranch_vccnz .LBB0_2104
	s_mov_b64 s[12:13], 0
	global_store_dwordx4 v[182:183], v[140:143], off offset:512 nt

.LBB0_2134:


	ds_read_b64 v[140:141], v205
	s_and_b64 vcc, exec, s[44:45]
	s_mov_b64 s[12:13], -1
	s_waitcnt lgkmcnt(0)
	v_sub_f32_e32 v143, v21, v140
	v_sub_f32_e32 v142, v20, v140
	v_sub_f32_e32 v147, v23, v140
	v_sub_f32_e32 v146, v22, v140
	v_pk_mul_f32 v[146:147], v[140:141], v[146:147] op_sel:[1,0]
	v_pk_mul_f32 v[140:141], v[140:141], v[142:143] op_sel:[1,0]
	s_waitcnt vmcnt(8)
	v_pk_fma_f32 v[142:143], v[230:231], v[146:147], v[234:235]
	v_pk_fma_f32 v[140:141], v[228:229], v[140:141], v[232:233]
	v_cndmask_b32_e64 v143, v224, v143, s[42:43]
	v_cndmask_b32_e64 v142, v224, v142, s[42:43]
	v_cndmask_b32_e64 v141, v224, v141, s[42:43]
	v_cndmask_b32_e64 v140, v224, v140, s[42:43]
	s_cbranch_vccnz .LBB0_2136
	s_mov_b64 s[12:13], 0
	global_store_dwordx4 v[182:183], v[140:143], off offset:576 nt

.LBB0_2138:
	ds_read_b64 v[140:141], v205 offset:128
	s_and_b64 vcc, exec, s[44:45]
	s_mov_b64 s[12:13], -1
	s_waitcnt lgkmcnt(0)
	v_sub_f32_e32 v143, v29, v140
	v_sub_f32_e32 v142, v28, v140
	v_sub_f32_e32 v147, v31, v140
	v_sub_f32_e32 v146, v30, v140
	v_pk_mul_f32 v[146:147], v[140:141], v[146:147] op_sel:[1,0]
	v_pk_mul_f32 v[140:141], v[140:141], v[142:143] op_sel:[1,0]
	v_pk_fma_f32 v[142:143], v[230:231], v[146:147], v[234:235]
	v_pk_fma_f32 v[140:141], v[228:229], v[140:141], v[232:233]
	v_cndmask_b32_e64 v143, v224, v143, s[42:43]
	v_cndmask_b32_e64 v142, v224, v142, s[42:43]
	v_cndmask_b32_e64 v141, v224, v141, s[42:43]
	v_cndmask_b32_e64 v140, v224, v140, s[42:43]
	s_cbranch_vccnz .LBB0_2140
	s_mov_b64 s[12:13], 0
	global_store_dwordx4 v[184:185], v[140:143], off offset:576 nt

.LBB0_2142:
	ds_read_b64 v[140:141], v205 offset:256
	s_and_b64 vcc, exec, s[44:45]
	s_mov_b64 s[12:13], -1
	s_waitcnt lgkmcnt(0)
	v_sub_f32_e32 v143, v45, v140
	v_sub_f32_e32 v142, v44, v140
	v_sub_f32_e32 v147, v47, v140
	v_sub_f32_e32 v146, v46, v140
	v_pk_mul_f32 v[146:147], v[140:141], v[146:147] op_sel:[1,0]
	v_pk_mul_f32 v[140:141], v[140:141], v[142:143] op_sel:[1,0]
	v_pk_fma_f32 v[142:143], v[230:231], v[146:147], v[234:235]
	v_pk_fma_f32 v[140:141], v[228:229], v[140:141], v[232:233]
	v_cndmask_b32_e64 v143, v224, v143, s[42:43]
	v_cndmask_b32_e64 v142, v224, v142, s[42:43]
	v_cndmask_b32_e64 v141, v224, v141, s[42:43]
	v_cndmask_b32_e64 v140, v224, v140, s[42:43]
	s_cbranch_vccnz .LBB0_2144
	s_mov_b64 s[12:13], 0
	global_store_dwordx4 v[186:187], v[140:143], off offset:576 nt

.LBB0_2146:
	ds_read_b64 v[140:141], v205 offset:384
	s_and_b64 vcc, exec, s[44:45]
	s_mov_b64 s[12:13], -1
	s_waitcnt lgkmcnt(0)
	v_sub_f32_e32 v143, v61, v140
	v_sub_f32_e32 v142, v60, v140
	v_sub_f32_e32 v147, v63, v140
	v_sub_f32_e32 v146, v62, v140
	v_pk_mul_f32 v[146:147], v[140:141], v[146:147] op_sel:[1,0]
	v_pk_mul_f32 v[140:141], v[140:141], v[142:143] op_sel:[1,0]
	v_pk_fma_f32 v[142:143], v[230:231], v[146:147], v[234:235]
	v_pk_fma_f32 v[140:141], v[228:229], v[140:141], v[232:233]
	v_cndmask_b32_e64 v143, v224, v143, s[42:43]
	v_cndmask_b32_e64 v142, v224, v142, s[42:43]
	v_cndmask_b32_e64 v141, v224, v141, s[42:43]
	v_cndmask_b32_e64 v140, v224, v140, s[42:43]
	s_cbranch_vccnz .LBB0_2148
	s_mov_b64 s[12:13], 0
	global_store_dwordx4 v[188:189], v[140:143], off offset:576 nt

.LBB0_2150:
	ds_read_b64 v[140:141], v205 offset:1024
	s_and_b64 vcc, exec, s[44:45]
	s_mov_b64 s[12:13], -1
	s_waitcnt lgkmcnt(0)
	v_sub_f32_e32 v143, v81, v140
	v_sub_f32_e32 v142, v80, v140
	v_sub_f32_e32 v147, v83, v140
	v_sub_f32_e32 v146, v82, v140
	v_pk_mul_f32 v[146:147], v[140:141], v[146:147] op_sel:[1,0]
	v_pk_mul_f32 v[140:141], v[140:141], v[142:143] op_sel:[1,0]
	v_pk_fma_f32 v[142:143], v[230:231], v[146:147], v[234:235]
	v_pk_fma_f32 v[140:141], v[228:229], v[140:141], v[232:233]
	v_cndmask_b32_e64 v143, v224, v143, s[42:43]
	v_cndmask_b32_e64 v142, v224, v142, s[42:43]
	v_cndmask_b32_e64 v141, v224, v141, s[42:43]
	v_cndmask_b32_e64 v140, v224, v140, s[42:43]
	s_cbranch_vccnz .LBB0_2152
	s_mov_b64 s[12:13], 0
	global_store_dwordx4 v[190:191], v[140:143], off offset:576 nt

.LBB0_2154:
	ds_read_b64 v[140:141], v205 offset:1152
	s_and_b64 vcc, exec, s[44:45]
	s_mov_b64 s[12:13], -1
	s_waitcnt lgkmcnt(0)
	v_sub_f32_e32 v143, v97, v140
	v_sub_f32_e32 v142, v96, v140
	v_sub_f32_e32 v147, v99, v140
	v_sub_f32_e32 v146, v98, v140
	v_pk_mul_f32 v[146:147], v[140:141], v[146:147] op_sel:[1,0]
	v_pk_mul_f32 v[140:141], v[140:141], v[142:143] op_sel:[1,0]
	v_pk_fma_f32 v[142:143], v[230:231], v[146:147], v[234:235]
	v_pk_fma_f32 v[140:141], v[228:229], v[140:141], v[232:233]
	v_cndmask_b32_e64 v143, v224, v143, s[42:43]
	v_cndmask_b32_e64 v142, v224, v142, s[42:43]
	v_cndmask_b32_e64 v141, v224, v141, s[42:43]
	v_cndmask_b32_e64 v140, v224, v140, s[42:43]
	s_cbranch_vccnz .LBB0_2156
	s_mov_b64 s[12:13], 0
	global_store_dwordx4 v[192:193], v[140:143], off offset:576 nt

.LBB0_2158:
	ds_read_b64 v[140:141], v205 offset:1280
	s_and_b64 vcc, exec, s[44:45]
	s_mov_b64 s[12:13], -1
	s_waitcnt lgkmcnt(0)
	v_sub_f32_e32 v143, v113, v140
	v_sub_f32_e32 v142, v112, v140
	v_sub_f32_e32 v147, v115, v140
	v_sub_f32_e32 v146, v114, v140
	v_pk_mul_f32 v[146:147], v[140:141], v[146:147] op_sel:[1,0]
	v_pk_mul_f32 v[140:141], v[140:141], v[142:143] op_sel:[1,0]
	v_pk_fma_f32 v[142:143], v[230:231], v[146:147], v[234:235]
	v_pk_fma_f32 v[140:141], v[228:229], v[140:141], v[232:233]
	v_cndmask_b32_e64 v143, v224, v143, s[42:43]
	v_cndmask_b32_e64 v142, v224, v142, s[42:43]
	v_cndmask_b32_e64 v141, v224, v141, s[42:43]
	v_cndmask_b32_e64 v140, v224, v140, s[42:43]
	s_cbranch_vccnz .LBB0_2160
	s_mov_b64 s[12:13], 0
	global_store_dwordx4 v[194:195], v[140:143], off offset:576 nt

.LBB0_2162:
	ds_read_b64 v[140:141], v205 offset:1408
	s_and_b64 vcc, exec, s[44:45]
	s_mov_b64 s[12:13], -1
	s_waitcnt lgkmcnt(0)
	v_sub_f32_e32 v143, v129, v140
	v_sub_f32_e32 v142, v128, v140
	v_sub_f32_e32 v147, v131, v140
	v_sub_f32_e32 v146, v130, v140
	v_pk_mul_f32 v[146:147], v[140:141], v[146:147] op_sel:[1,0]
	v_pk_mul_f32 v[140:141], v[140:141], v[142:143] op_sel:[1,0]
	v_pk_fma_f32 v[230:231], v[230:231], v[146:147], v[234:235]
	v_pk_fma_f32 v[228:229], v[228:229], v[140:141], v[232:233]
	v_cndmask_b32_e64 v231, v224, v231, s[42:43]
	v_cndmask_b32_e64 v230, v224, v230, s[42:43]
	v_cndmask_b32_e64 v229, v224, v229, s[42:43]
	v_cndmask_b32_e64 v228, v224, v228, s[42:43]
	s_cbranch_vccnz .LBB0_2164
	s_mov_b64 s[12:13], 0
	global_store_dwordx4 v[196:197], v[228:231], off offset:576 nt
.LBB0_2164:
	s_andn2_b64 vcc, exec, s[12:13]
	s_cbranch_vccnz .LBB0_2166
	v_lshl_add_u64 v[66:67], v[180:181], 0, v[66:67]
	v_lshl_add_u64 v[66:67], v[66:67], 1, s[10:11]
	v_cvt_pk_bf16_f32 v228, v228, v229
	v_cvt_pk_bf16_f32 v229, v230, v231
	global_store_dwordx2 v[66:67], v[228:229], off
